# E23 with 6 waves converting in waiting mode (was 5)
# baseline (speedup 1.0000x reference)
.LBB0_70:
	v_mov_b32_e32 v2, s72
	ds_read_b32 v2, v2
	s_mov_b32 s2, 0x3307f
	s_waitcnt lgkmcnt(0)
	v_cmp_lt_u32_e32 vcc, s2, v2
	v_mov_b32_e32 v2, -1
	s_cbranch_vccnz .LBB0_76
	global_load_dword v4, v67, s[66:67] sc1
	v_add_u32_e32 v3, -1, v3
	v_mov_b32_e32 v2, -1
	s_waitcnt vmcnt(0)
	v_cmp_eq_u32_e32 vcc, v4, v3
	s_and_saveexec_b64 s[26:27], vcc
	s_cbranch_execz .LBB0_75
	s_mov_b64 s[28:29], exec
	v_mbcnt_lo_u32_b32 v2, s28, 0
	v_mbcnt_hi_u32_b32 v2, s29, v2
	v_cmp_eq_u32_e32 vcc, 0, v2
	s_and_saveexec_b64 s[6:7], vcc
	s_cbranch_execz .LBB0_74
	s_bcnt1_i32_b64 s2, s[28:29]
	s_mul_i32 s2, s2, 6
	v_mov_b32_e32 v3, s2
	global_atomic_add v3, v67, v3, s[24:25] sc0
.LBB0_74:
	s_or_b64 exec, exec, s[6:7]
	s_waitcnt vmcnt(0)
	v_readfirstlane_b32 s2, v3
	v_mov_b32_e32 v4, s72
	s_nop 0
	v_mad_u32_u24 v2, v2, 6, s2
	v_add_u32_e32 v3, 6, v2
	ds_write_b32 v4, v3
	v_mov_b32_e32 v3, s33
	v_mov_b32_e32 v4, 6
	ds_write_b32 v3, v4

.LBB0_365:
	v_readlane_b32 s2, v252, 24
	s_nop 1
	v_mov_b32_e32 v2, s2
	ds_read_b32 v2, v2
	s_mov_b32 s2, 0x3307f
	s_waitcnt lgkmcnt(0)
	v_cmp_lt_u32_e32 vcc, s2, v2
	v_mov_b32_e32 v2, -1
	s_cbranch_vccnz .LBB0_371
	v_readlane_b32 s12, v252, 34
	v_readlane_b32 s13, v252, 35
	v_add_u32_e32 v3, -1, v3
	v_mov_b32_e32 v2, -1
	s_nop 2
	global_load_dword v4, v147, s[12:13] sc1
	s_waitcnt vmcnt(0)
	v_cmp_eq_u32_e32 vcc, v4, v3
	s_and_saveexec_b64 s[18:19], vcc
	s_cbranch_execz .LBB0_370
	s_mov_b64 s[36:37], exec
	v_mbcnt_lo_u32_b32 v2, s36, 0
	v_mbcnt_hi_u32_b32 v2, s37, v2
	v_cmp_eq_u32_e32 vcc, 0, v2
	s_and_saveexec_b64 s[30:31], vcc
	s_cbranch_execz .LBB0_369
	s_bcnt1_i32_b64 s2, s[36:37]
	s_mul_i32 s2, s2, 6
	v_mov_b32_e32 v3, s2
	global_atomic_add v3, v147, v3, s[34:35] sc0
.LBB0_369:
	s_or_b64 exec, exec, s[30:31]
	s_waitcnt vmcnt(0)
	v_readfirstlane_b32 s2, v3
	s_nop 1
	v_mad_u32_u24 v2, v2, 6, s2
	v_readlane_b32 s2, v252, 24
	v_add_u32_e32 v3, 6, v2
	s_nop 0
	v_mov_b32_e32 v4, s2
	v_readlane_b32 s2, v252, 22
	ds_write_b32 v4, v3
	s_nop 0
	v_mov_b32_e32 v3, s2
	v_mov_b32_e32 v4, 6
	ds_write_b32 v3, v4
